# 8 fixes: + gla_prep Q/K/V prefetch, gla_norm sample tail batched
# baseline (speedup 1.0000x reference)
; #define LAS __attribute__((address_space(3)))
; __device__ __forceinline__ unsigned cvtpk(float lo, float hi) { unsigned r; asm volatile("v_cvt_pk_bf16_f32 %0, %1, %2" : "=v"(r) : "v"(lo), "v"(hi)); return r; }
; #define MFMA16(a, b, c) __builtin_amdgcn_mfma_f32_16x16x32_bf16((a), (b), (c), 0, 0, 0)
; __device__ __forceinline__ void phase_gla_prep(KArgs a, LAS unsigned char* lds, int tid, int wave, int lane) {
;     ...
;                 for (int j = 0; j < 4; ++j) if (s0 + j > t) acc[j] = 0.f;
;                 u32x2 w; w.x = cvtpk(acc[0], acc[1]); w.y = cvtpk(acc[2], acc[3]); *(LAS u32x2*)(SC + t * SC_LD + s0) = w; }
;         }
;         __syncthreads();
;         for (int hv = 0; hv < 2; ++hv) {
;             const int t = lane;
; #pragma unroll
;             for (int i = 0; i < 4; ++i) { const int vg = wave + 8 * i, v0 = vg * 8; const u32x4 w = *(const u32x4*)(V + (row0 + t) * DM + h * 512 + hv * 256 + v0);
;                 LAS bf16* d = VTs + v0 * VT_LD + t;
;                 d[0] = (bf16)(w.x & 0xffffu); d[VT_LD] = (bf16)(w.x >> 16); d[2 * VT_LD] = (bf16)(w.y & 0xffffu); d[3 * VT_LD] = (bf16)(w.y >> 16);
;                 d[4 * VT_LD] = (bf16)(w.z & 0xffffu); d[5 * VT_LD] = (bf16)(w.z >> 16); d[6 * VT_LD] = (bf16)(w.w & 0xffffu); d[7 * VT_LD] = (bf16)(w.w >> 16); }
;             __syncthreads();
; #pragma unroll
;             for (int i = 0; i < 4; ++i) { const int p = tid + 512 * i, v = p >> 3, c8 = p & 7;
;                 *(u32x4*)(VTg + ((((size_t)item * 32 + hv * 16 + (v >> 4)) * 2 + (c8 >> 2)) * 64 + (c8 & 3) * 16 + (v & 15)) * 8) = *(const LAS u32x4*)(VTs + v * VT_LD + c8 * 8); }
; #pragma unroll
;             for (int i = 0; i < 8; ++i) { const int vb = wave * 2 + (i >> 2), tb = i & 3; f32x4 acc = (f32x4){0.f, 0.f, 0.f, 0.f};
; #pragma unroll
;                 for (int st = 0; st < 2; ++st) { const bf16x8 av = *(const LAS bf16x8*)(VTs + (vb * 16 + l16) * VT_LD + st * 32 + g4 * 8), bv = *(const LAS bf16x8*)(SC + (tb * 16 + l16) * SC_LD + st * 32 + g4 * 8);
;                     acc = MFMA16(av, bv, acc); }
;                 *(f32x4*)(O + ((((size_t)item * 32 + hv * 16 + vb) * 4 + tb) * 64 + lane) * 4) = acc; }
.LBB0_822:
	s_nop 6
	v_cndmask_b32_e64 v6, v2, 0, s[16:17]
	v_cndmask_b32_e64 v3, 0, v3, s[18:19]
	v_cndmask_b32_e64 v2, v6, v2, s[18:19]
	v_cndmask_b32_e64 v4, v4, 0, s[20:21]
	v_cndmask_b32_e64 v5, v5, 0, s[22:23]
	v_cvt_pk_bf16_f32 v2, v2, v3
	v_cvt_pk_bf16_f32 v3, v4, v5
	ds_write_b64 v57, v[2:3]
	v_lshlrev_b64 v[2:3], 12, v[42:43]
	v_lshl_add_u64 v[2:3], s[94:95], 0, v[2:3]
	v_lshl_add_u64 v[2:3], v[2:3], 0, s[48:49]
	v_lshl_add_u64 v[2:3], s[28:29], 1, v[2:3]
	s_waitcnt lgkmcnt(0)
	s_barrier
	v_add_u32_e32 v5, s57, v48
	s_mul_i32 s48, s58, 0x90
	v_add_u32_e32 v4, s48, v48
	s_lshl_b64 s[70:71], s[68:69], 5
	v_lshl_add_u64 v[10:11], s[70:71], 0, v[30:31]
	v_lshlrev_b64 v[10:11], 11, v[10:11]
	v_or_b32_e32 v10, v10, v59
	v_lshl_add_u64 v[10:11], s[96:97], 0, v[10:11]
	s_add_u32 s90, s70, s2
	s_addc_u32 s91, s71, s66
	s_lshl_b64 s[90:91], s[90:91], 12
	v_lshl_add_u64 v[94:95], v[38:39], 0, s[90:91]
	s_add_u32 s90, s70, s67
	s_addc_u32 s91, s71, s73
	s_lshl_b64 s[90:91], s[90:91], 12
	ds_write_b16 v5, v128
	ds_write_b16_d16_hi v5, v128 offset:144
	ds_write_b16 v5, v129 offset:288
	ds_write_b16_d16_hi v5, v129 offset:432
	ds_write_b16 v5, v130 offset:576
	ds_write_b16_d16_hi v5, v130 offset:720
	ds_write_b16 v5, v131 offset:864
	ds_write_b16_d16_hi v5, v131 offset:1008
	ds_write_b16 v4, v132
	ds_write_b16_d16_hi v4, v132 offset:144
	ds_write_b16 v4, v133 offset:288
	ds_write_b16_d16_hi v4, v133 offset:432
	ds_write_b16 v4, v134 offset:576
	ds_write_b16_d16_hi v4, v134 offset:720
	ds_write_b16 v4, v135 offset:864
	ds_write_b16_d16_hi v4, v135 offset:1008
	ds_write_b16 v4, v136 offset:9216
	ds_write_b16_d16_hi v4, v136 offset:9360
	ds_write_b16 v4, v137 offset:9504
	ds_write_b16_d16_hi v4, v137 offset:9648
	ds_write_b16 v4, v138 offset:9792
	ds_write_b16_d16_hi v4, v138 offset:9936
	ds_write_b16 v4, v139 offset:10080
	ds_write_b16_d16_hi v4, v139 offset:10224
	ds_write_b16 v4, v140 offset:18432
	ds_write_b16_d16_hi v4, v140 offset:18576
	ds_write_b16 v4, v141 offset:18720
	ds_write_b16_d16_hi v4, v141 offset:18864
	ds_write_b16 v4, v142 offset:19008
	ds_write_b16_d16_hi v4, v142 offset:19152
	ds_write_b16 v4, v143 offset:19296
	ds_write_b16_d16_hi v4, v143 offset:19440
	s_waitcnt lgkmcnt(0)
	s_barrier
	ds_read_b128 v[6:9], v58
	s_waitcnt lgkmcnt(0)
	global_store_dwordx4 v[10:11], v[6:9], off
	ds_read_b128 v[6:9], v60
	v_lshl_add_u64 v[10:11], s[70:71], 0, v[32:33]
	v_lshlrev_b64 v[10:11], 11, v[10:11]
	v_or_b32_e32 v10, v10, v61
	v_lshl_add_u64 v[10:11], s[96:97], 0, v[10:11]
	s_waitcnt lgkmcnt(0)
	global_store_dwordx4 v[10:11], v[6:9], off
	ds_read_b128 v[6:9], v62
	v_lshl_add_u64 v[10:11], s[70:71], 0, v[34:35]
	v_lshlrev_b64 v[10:11], 11, v[10:11]
	v_or_b32_e32 v10, v10, v63
	v_lshl_add_u64 v[10:11], s[96:97], 0, v[10:11]
	s_waitcnt lgkmcnt(0)
	global_store_dwordx4 v[10:11], v[6:9], off
	ds_read_b128 v[6:9], v64
	v_lshl_add_u64 v[10:11], s[70:71], 0, v[36:37]
	v_lshlrev_b64 v[10:11], 11, v[10:11]
	v_or_b32_e32 v10, v10, v65
	v_lshl_add_u64 v[10:11], s[96:97], 0, v[10:11]
	s_waitcnt lgkmcnt(0)
	global_store_dwordx4 v[10:11], v[6:9], off
	ds_read_b128 v[6:9], v66
	ds_read_b128 v[10:13], v67
	ds_read_b128 v[42:45], v66 offset:64
	ds_read_b128 v[70:73], v67 offset:64
	s_waitcnt lgkmcnt(2)
	v_mfma_f32_16x16x32_bf16 v[14:17], v[6:9], v[10:13], 0
	ds_read_b128 v[78:81], v67 offset:2368
	s_or_b32 s70, s70, 16
	ds_read_b128 v[86:89], v67 offset:4672
	s_waitcnt lgkmcnt(2)
	v_mfma_f32_16x16x32_bf16 v[14:17], v[42:45], v[70:73], v[14:17]
	ds_read_b128 v[90:93], v68 offset:64
	s_nop 6
	global_store_dwordx4 v[94:95], v[14:17], off
	ds_read_b128 v[14:17], v67 offset:2304
	s_waitcnt lgkmcnt(0)
	v_mfma_f32_16x16x32_bf16 v[74:77], v[6:9], v[14:17], 0
	v_mfma_f32_16x16x32_bf16 v[74:77], v[42:45], v[78:81], v[74:77]
	s_nop 7
	global_store_dwordx4 v[94:95], v[74:77], off offset:1024
	ds_read_b128 v[74:77], v67 offset:4608
	s_waitcnt lgkmcnt(0)
	v_mfma_f32_16x16x32_bf16 v[82:85], v[6:9], v[74:77], 0
	v_mfma_f32_16x16x32_bf16 v[82:85], v[42:45], v[86:89], v[82:85]
	s_nop 7
	global_store_dwordx4 v[94:95], v[82:85], off offset:2048
	ds_read_b128 v[82:85], v68
	s_waitcnt lgkmcnt(0)
	v_mfma_f32_16x16x32_bf16 v[6:9], v[6:9], v[82:85], 0
	v_mfma_f32_16x16x32_bf16 v[6:9], v[42:45], v[90:93], v[6:9]
	ds_read_b128 v[42:45], v69 offset:64
	s_nop 6
	global_store_dwordx4 v[94:95], v[6:9], off offset:3072
	ds_read_b128 v[6:9], v69
	s_waitcnt lgkmcnt(0)
	v_mfma_f32_16x16x32_bf16 v[10:13], v[6:9], v[10:13], 0
	v_mfma_f32_16x16x32_bf16 v[10:13], v[42:45], v[70:73], v[10:13]
	v_lshl_add_u64 v[70:71], v[38:39], 0, s[90:91]
	s_add_u32 s90, s70, s2
	s_addc_u32 s91, s71, s66
	s_lshl_b64 s[90:91], s[90:91], 12
	s_nop 3
	global_store_dwordx4 v[70:71], v[10:13], off
	s_nop 1
	v_mfma_f32_16x16x32_bf16 v[10:13], v[6:9], v[14:17], 0
	v_mfma_f32_16x16x32_bf16 v[10:13], v[42:45], v[78:81], v[10:13]
	s_nop 7
	global_store_dwordx4 v[70:71], v[10:13], off offset:1024
	s_nop 1
	v_mfma_f32_16x16x32_bf16 v[10:13], v[6:9], v[74:77], 0
	v_mfma_f32_16x16x32_bf16 v[6:9], v[6:9], v[82:85], 0
	v_mfma_f32_16x16x32_bf16 v[10:13], v[42:45], v[86:89], v[10:13]
	v_mfma_f32_16x16x32_bf16 v[6:9], v[42:45], v[90:93], v[6:9]
	v_lshl_add_u64 v[90:91], v[38:39], 0, s[90:91]
	s_nop 5
	global_store_dwordx4 v[70:71], v[10:13], off offset:2048
	global_store_dwordx4 v[70:71], v[6:9], off offset:3072
	s_barrier
; #define LAS __attribute__((address_space(3)))
; #define MFMA16(a, b, c) __builtin_amdgcn_mfma_f32_16x16x32_bf16((a), (b), (c), 0, 0, 0)
; __device__ __forceinline__ void phase_gla_prep(KArgs a, LAS unsigned char* lds, int tid, int wave, int lane) {
;     ...
;         for (int hv = 0; hv < 2; ++hv) {
;             const int t = lane;
; #pragma unroll
;             for (int i = 0; i < 4; ++i) { const int vg = wave + 8 * i, v0 = vg * 8; const u32x4 w = *(const u32x4*)(V + (row0 + t) * DM + h * 512 + hv * 256 + v0);
;                 LAS bf16* d = VTs + v0 * VT_LD + t;
;                 d[0] = (bf16)(w.x & 0xffffu); d[VT_LD] = (bf16)(w.x >> 16); d[2 * VT_LD] = (bf16)(w.y & 0xffffu); d[3 * VT_LD] = (bf16)(w.y >> 16);
;                 d[4 * VT_LD] = (bf16)(w.z & 0xffffu); d[5 * VT_LD] = (bf16)(w.z >> 16); d[6 * VT_LD] = (bf16)(w.w & 0xffffu); d[7 * VT_LD] = (bf16)(w.w >> 16); }
;             __syncthreads();
; #pragma unroll
;             for (int i = 0; i < 4; ++i) { const int p = tid + 512 * i, v = p >> 3, c8 = p & 7;
;                 *(u32x4*)(VTg + ((((size_t)item * 32 + hv * 16 + (v >> 4)) * 2 + (c8 >> 2)) * 64 + (c8 & 3) * 16 + (v & 15)) * 8) = *(const LAS u32x4*)(VTs + v * VT_LD + c8 * 8); }
; #pragma unroll
;             for (int i = 0; i < 8; ++i) { const int vb = wave * 2 + (i >> 2), tb = i & 3; f32x4 acc = (f32x4){0.f, 0.f, 0.f, 0.f};
; #pragma unroll
;                 for (int st = 0; st < 2; ++st) { const bf16x8 av = *(const LAS bf16x8*)(VTs + (vb * 16 + l16) * VT_LD + st * 32 + g4 * 8), bv = *(const LAS bf16x8*)(SC + (tb * 16 + l16) * SC_LD + st * 32 + g4 * 8);
;                     acc = MFMA16(av, bv, acc); }
;                 *(f32x4*)(O + ((((size_t)item * 32 + hv * 16 + vb) * 4 + tb) * 64 + lane) * 4) = acc; }
;             __syncthreads();
;         }
;     }
	ds_write_b16 v5, v144
	ds_write_b16_d16_hi v5, v144 offset:144
	ds_write_b16 v5, v145 offset:288
	ds_write_b16_d16_hi v5, v145 offset:432
	ds_write_b16 v5, v146 offset:576
	ds_write_b16_d16_hi v5, v146 offset:720
	ds_write_b16 v5, v147 offset:864
	ds_write_b16_d16_hi v5, v147 offset:1008
	ds_write_b16 v4, v148
	ds_write_b16_d16_hi v4, v148 offset:144
	ds_write_b16 v4, v149 offset:288
	ds_write_b16_d16_hi v4, v149 offset:432
	ds_write_b16 v4, v150 offset:576
	ds_write_b16_d16_hi v4, v150 offset:720
	ds_write_b16 v4, v151 offset:864
	ds_write_b16_d16_hi v4, v151 offset:1008
	ds_write_b16 v4, v152 offset:9216
	ds_write_b16_d16_hi v4, v152 offset:9360
	ds_write_b16 v4, v153 offset:9504
	ds_write_b16_d16_hi v4, v153 offset:9648
	ds_write_b16 v4, v154 offset:9792
	ds_write_b16_d16_hi v4, v154 offset:9936
	ds_write_b16 v4, v155 offset:10080
	ds_write_b16_d16_hi v4, v155 offset:10224
	ds_write_b16 v4, v156 offset:18432
	ds_write_b16_d16_hi v4, v156 offset:18576
	ds_write_b16 v4, v157 offset:18720
	ds_write_b16_d16_hi v4, v157 offset:18864
	ds_write_b16 v4, v158 offset:19008
	ds_write_b16_d16_hi v4, v158 offset:19152
	ds_write_b16 v4, v159 offset:19296
	ds_write_b16_d16_hi v4, v159 offset:19440
	s_waitcnt lgkmcnt(0)
	s_barrier
	ds_read_b128 v[2:5], v58
	v_lshl_add_u64 v[6:7], s[70:71], 0, v[30:31]
	v_lshlrev_b64 v[6:7], 11, v[6:7]
	v_or_b32_e32 v6, v6, v59
	v_lshl_add_u64 v[6:7], s[96:97], 0, v[6:7]
	s_waitcnt lgkmcnt(0)
	global_store_dwordx4 v[6:7], v[2:5], off
	ds_read_b128 v[2:5], v60
	v_lshl_add_u64 v[6:7], s[70:71], 0, v[32:33]
	v_lshlrev_b64 v[6:7], 11, v[6:7]
	v_or_b32_e32 v6, v6, v61
	v_lshl_add_u64 v[6:7], s[96:97], 0, v[6:7]
	s_waitcnt lgkmcnt(0)
	global_store_dwordx4 v[6:7], v[2:5], off
	ds_read_b128 v[2:5], v62
	v_lshl_add_u64 v[6:7], s[70:71], 0, v[34:35]
	v_lshlrev_b64 v[6:7], 11, v[6:7]
	v_or_b32_e32 v6, v6, v63
	v_lshl_add_u64 v[6:7], s[96:97], 0, v[6:7]
	s_waitcnt lgkmcnt(0)
	global_store_dwordx4 v[6:7], v[2:5], off
	ds_read_b128 v[2:5], v64
	v_lshl_add_u64 v[6:7], s[70:71], 0, v[36:37]
	v_lshlrev_b64 v[6:7], 11, v[6:7]
	v_or_b32_e32 v6, v6, v65
	v_lshl_add_u64 v[6:7], s[96:97], 0, v[6:7]
	s_waitcnt lgkmcnt(0)
	global_store_dwordx4 v[6:7], v[2:5], off
	ds_read_b128 v[2:5], v66
	ds_read_b128 v[6:9], v67
	ds_read_b128 v[14:17], v66 offset:64
	ds_read_b128 v[42:45], v67 offset:64
	s_waitcnt lgkmcnt(2)
	v_mfma_f32_16x16x32_bf16 v[10:13], v[2:5], v[6:9], 0
	ds_read_b128 v[74:77], v67 offset:2368
	ds_read_b128 v[82:85], v67 offset:4672
	ds_read_b128 v[86:89], v68 offset:64
	s_waitcnt lgkmcnt(3)
	v_mfma_f32_16x16x32_bf16 v[10:13], v[14:17], v[42:45], v[10:13]
	s_add_u32 s70, s70, s67
	s_addc_u32 s71, s71, s73
	s_lshl_b64 s[70:71], s[70:71], 12
	s_nop 4
	global_store_dwordx4 v[90:91], v[10:13], off
	ds_read_b128 v[10:13], v67 offset:2304
	s_waitcnt lgkmcnt(0)
	v_mfma_f32_16x16x32_bf16 v[70:73], v[2:5], v[10:13], 0
	v_mfma_f32_16x16x32_bf16 v[70:73], v[14:17], v[74:77], v[70:73]
	s_nop 7
	global_store_dwordx4 v[90:91], v[70:73], off offset:1024
	ds_read_b128 v[70:73], v67 offset:4608
	s_waitcnt lgkmcnt(0)
	v_mfma_f32_16x16x32_bf16 v[78:81], v[2:5], v[70:73], 0
	v_mfma_f32_16x16x32_bf16 v[78:81], v[14:17], v[82:85], v[78:81]
	s_nop 7
	global_store_dwordx4 v[90:91], v[78:81], off offset:2048
	ds_read_b128 v[78:81], v68
	s_waitcnt lgkmcnt(0)
	v_mfma_f32_16x16x32_bf16 v[2:5], v[2:5], v[78:81], 0
	v_mfma_f32_16x16x32_bf16 v[2:5], v[14:17], v[86:89], v[2:5]
	ds_read_b128 v[14:17], v69 offset:64
	s_nop 6
	global_store_dwordx4 v[90:91], v[2:5], off offset:3072
	ds_read_b128 v[2:5], v69
	s_waitcnt lgkmcnt(0)
	v_mfma_f32_16x16x32_bf16 v[6:9], v[2:5], v[6:9], 0
	v_mfma_f32_16x16x32_bf16 v[6:9], v[14:17], v[42:45], v[6:9]
	v_lshl_add_u64 v[42:43], v[38:39], 0, s[70:71]
	s_nop 6
	global_store_dwordx4 v[42:43], v[6:9], off
	s_nop 1
	v_mfma_f32_16x16x32_bf16 v[6:9], v[2:5], v[10:13], 0
	v_mfma_f32_16x16x32_bf16 v[6:9], v[14:17], v[74:77], v[6:9]
	s_nop 7
	global_store_dwordx4 v[42:43], v[6:9], off offset:1024
	s_nop 1
	v_mfma_f32_16x16x32_bf16 v[6:9], v[2:5], v[70:73], 0
	v_mfma_f32_16x16x32_bf16 v[2:5], v[2:5], v[78:81], 0
	v_mfma_f32_16x16x32_bf16 v[6:9], v[14:17], v[82:85], v[6:9]
	v_mfma_f32_16x16x32_bf16 v[2:5], v[14:17], v[86:89], v[2:5]
	s_nop 6
	global_store_dwordx4 v[42:43], v[6:9], off offset:2048
	global_store_dwordx4 v[42:43], v[2:5], off offset:3072
	s_barrier
	s_load_dword s48, s[0:1], 0x120
	s_waitcnt lgkmcnt(0)
	s_add_i32 s68, s68, s48
	s_cmpk_lt_i32 s68, 0x200
	s_cbranch_scc0 .LBB0_835

; #define LAS __attribute__((address_space(3)))
; __device__ __forceinline__ void phase_gla_prep(KArgs a, LAS unsigned char* lds, int tid, int wave, int lane) {
;     ...
;             const int k = tid & 255, hf = tid >> 8; float w2[16];
; #pragma unroll
;             for (int r = 0; r < 16; ++r) w2[r] = wg2[(size_t)r * 1024 + h * 256 + k];
;             const float bgk = bg[h * 256 + k]; float cum = 0.f;
;             for (int t = 0; t < 32; ++t) { const int tt = hf * 32 + t; float z = bgk;
; #pragma unroll
;                 for (int r4 = 0; r4 < 4; ++r4) { const f32x4 gv = *(const LAS f32x4*)(g1s + tt * 16 + r4 * 4); z += gv[0] * w2[r4 * 4] + gv[1] * w2[r4 * 4 + 1] + gv[2] * w2[r4 * 4 + 2] + gv[3] * w2[r4 * 4 + 3]; }
;                 const float ls = fminf(z, 0.f) - log1pf(__expf(-fabsf(z)));
;                 cum += ls * 0.0625f; BC[tt * BC_LD + k] = cum; }
;             __syncthreads();
;             if (hf == 1) { const float tot0 = BC[31 * BC_LD + k];
;                 for (int t = 32; t < 64; ++t) BC[t * BC_LD + k] += tot0; }
;             __syncthreads();
;         }
;         {
;             const int t = lane;
; #pragma unroll
;             for (int i = 0; i < 4; ++i) { const int kg = wave + 8 * i, k0 = kg * 8; const size_t src = (row0 + t) * 1024 + h * 256 + k0;
;                 const u32x4 qw = *(const u32x4*)(Q + src), kw = *(const u32x4*)(Kf + src);
;     ...
;             for (int i = 0; i < 4; ++i) { const int vg = wave + 8 * i, v0 = vg * 8; const u32x4 w = *(const u32x4*)(V + (row0 + t) * DM + h * 512 + hv * 256 + v0);
.LBB0_825:
	s_or_b64 exec, exec, vcc
	s_bfe_u32 s48, s68, 0x20005
	s_lshl_b32 s69, s48, 8
	s_lshl_b32 s48, s48, 10
	v_lshl_add_u64 v[42:43], v[24:25], 0, s[48:49]
	v_add_co_u32_e32 v4, vcc, 0x1000, v42
	s_waitcnt lgkmcnt(0)
	s_nop 0
	v_addc_co_u32_e32 v5, vcc, 0, v43, vcc
	v_add_co_u32_e32 v6, vcc, s38, v42
	s_barrier
	s_nop 0
	v_addc_co_u32_e32 v7, vcc, 0, v43, vcc
	v_add_co_u32_e32 v8, vcc, 0x3000, v42
	s_nop 1
	v_addc_co_u32_e32 v9, vcc, 0, v43, vcc
	v_add_co_u32_e32 v10, vcc, s41, v42
	global_load_dword v2, v[42:43], off
	s_nop 0
	v_addc_co_u32_e32 v11, vcc, 0, v43, vcc
	global_load_dword v4, v[4:5], off
	s_mov_b32 s75, 0x8000
	global_load_dword v6, v[6:7], off
	s_nop 0
	global_load_dword v8, v[8:9], off
	s_nop 0
	global_load_dword v3, v[10:11], off
	v_add_co_u32_e32 v10, vcc, 0x5000, v42
	s_nop 1
	v_addc_co_u32_e32 v11, vcc, 0, v43, vcc
	global_load_dword v5, v[10:11], off
	v_add_co_u32_e32 v10, vcc, s42, v42
	s_nop 1
	v_addc_co_u32_e32 v11, vcc, 0, v43, vcc
	global_load_dword v7, v[10:11], off
	v_add_co_u32_e32 v10, vcc, 0x7000, v42
	s_nop 1
	v_addc_co_u32_e32 v11, vcc, 0, v43, vcc
	global_load_dword v9, v[10:11], off
	v_add_co_u32_e32 v10, vcc, s75, v42
	s_mov_b32 s75, 0xa000
	s_nop 0
	v_addc_co_u32_e32 v11, vcc, 0, v43, vcc
	v_add_co_u32_e32 v12, vcc, 0x9000, v42
	global_load_dword v10, v[10:11], off
	s_nop 0
	v_addc_co_u32_e32 v13, vcc, 0, v43, vcc
	v_add_co_u32_e32 v14, vcc, s75, v42
	s_mov_b32 s75, 0xc000
	s_nop 0
	v_addc_co_u32_e32 v15, vcc, 0, v43, vcc
	v_add_co_u32_e32 v16, vcc, 0xb000, v42
	global_load_dword v12, v[12:13], off
	s_nop 0
	v_addc_co_u32_e32 v17, vcc, 0, v43, vcc
	v_add_co_u32_e32 v44, vcc, s75, v42
	global_load_dword v14, v[14:15], off
	s_nop 0
	v_addc_co_u32_e32 v45, vcc, 0, v43, vcc
	global_load_dword v16, v[16:17], off
	s_mov_b32 s75, 0xe000
	global_load_dword v11, v[44:45], off
	v_add_co_u32_e32 v44, vcc, 0xd000, v42
	s_nop 1
	v_addc_co_u32_e32 v45, vcc, 0, v43, vcc
	global_load_dword v13, v[44:45], off
	v_add_co_u32_e32 v44, vcc, s75, v42
	s_mov_b32 s75, 32
	s_nop 0
	v_addc_co_u32_e32 v45, vcc, 0, v43, vcc
	v_add_co_u32_e32 v42, vcc, 0xf000, v42
	global_load_dword v15, v[44:45], off
	s_nop 0
	v_addc_co_u32_e32 v43, vcc, 0, v43, vcc
	global_load_dword v17, v[42:43], off
	v_or_b32_sdwa v42, s69, v18 dst_sel:DWORD dst_unused:UNUSED_PAD src0_sel:DWORD src1_sel:BYTE_0
	v_lshlrev_b32_e32 v42, 2, v42
	global_load_dword v42, v42, s[30:31]
	v_mov_b32_e32 v161, s71
	v_or_b32_e32 v160, s70, v20
	v_lshlrev_b64 v[162:163], 10, v[160:161]
	v_lshlrev_b64 v[170:171], 12, v[160:161]
	v_or_b32_e32 v162, s69, v162
	v_lshl_add_u64 v[170:171], s[94:95], 0, v[170:171]
	v_lshl_add_u64 v[164:165], v[162:163], 0, s[28:29]
	v_lshl_add_u64 v[170:171], v[170:171], 0, s[48:49]
	v_lshlrev_b64 v[164:165], 1, v[164:165]
	v_lshl_add_u64 v[170:171], s[28:29], 1, v[170:171]
	v_lshl_add_u64 v[166:167], s[54:55], 0, v[164:165]
	v_lshl_add_u64 v[168:169], s[92:93], 0, v[164:165]
	global_load_dwordx4 v[96:99], v[166:167], off
	global_load_dwordx4 v[100:103], v[168:169], off
	global_load_dwordx4 v[104:107], v[166:167], off offset:128
	global_load_dwordx4 v[108:111], v[168:169], off offset:128
	global_load_dwordx4 v[112:115], v[166:167], off offset:256
	global_load_dwordx4 v[116:119], v[168:169], off offset:256
	global_load_dwordx4 v[120:123], v[166:167], off offset:384
	global_load_dwordx4 v[124:127], v[168:169], off offset:384
	global_load_dwordx4 v[128:131], v[170:171], off
	global_load_dwordx4 v[132:135], v[170:171], off offset:128
	global_load_dwordx4 v[136:139], v[170:171], off offset:256
	global_load_dwordx4 v[140:143], v[170:171], off offset:384
	global_load_dwordx4 v[144:147], v[170:171], off offset:512
	global_load_dwordx4 v[148:151], v[170:171], off offset:640
	global_load_dwordx4 v[152:155], v[170:171], off offset:768
	global_load_dwordx4 v[156:159], v[170:171], off offset:896
	v_mov_b32_e32 v43, 0
	v_mov_b32_e32 v44, v52
	v_mov_b32_e32 v45, v0

; #define LAS __attribute__((address_space(3)))
; __device__ __forceinline__ void phase_gla_prep(KArgs a, LAS unsigned char* lds, int tid, int wave, int lane) {
;     ...
;             const int t = lane;
; #pragma unroll
;             for (int i = 0; i < 4; ++i) { const int kg = wave + 8 * i, k0 = kg * 8; const size_t src = (row0 + t) * 1024 + h * 256 + k0;
;                 const u32x4 qw = *(const u32x4*)(Q + src), kw = *(const u32x4*)(Kf + src);
;                 const f32x4 q0 = (f32x4){bflo(qw.x), bfhi(qw.x), bflo(qw.y), bfhi(qw.y)}, q1 = (f32x4){bflo(qw.z), bfhi(qw.z), bflo(qw.w), bfhi(qw.w)}, c0 = (f32x4){bflo(kw.x), bfhi(kw.x), bflo(kw.y), bfhi(kw.y)}, c1 = (f32x4){bflo(kw.z), bfhi(kw.z), bflo(kw.w), bfhi(kw.w)};
;                 const f32x4 b0 = *(const LAS f32x4*)(BC + t * BC_LD + k0), b1 = *(const LAS f32x4*)(BC + t * BC_LD + k0 + 4), l0 = *(const LAS f32x4*)(BC + 63 * BC_LD + k0), l1 = *(const LAS f32x4*)(BC + 63 * BC_LD + k0 + 4);
;                 f32x4 qi0, qi1, ki0, ki1, ke0, ke1;
; #pragma unroll
;                 for (int e = 0; e < 4; ++e) { const float ep0 = __expf(b0[e]), ep1 = __expf(b1[e]);
;                     qi0[e] = q0[e] * ep0; qi1[e] = q1[e] * ep1; ki0[e] = c0[e] * __expf(-b0[e]); ki1[e] = c1[e] * __expf(-b1[e]);
;                     ke0[e] = c0[e] * __expf(l0[e] - b0[e]); ke1[e] = c1[e] * __expf(l1[e] - b1[e]); }
;                 u32x4 wq; wq.x = cvtpk(qi0[0], qi0[1]); wq.y = cvtpk(qi0[2], qi0[3]); wq.z = cvtpk(qi1[0], qi1[1]); wq.w = cvtpk(qi1[2], qi1[3]);
;                 u32x4 wk; wk.x = cvtpk(ki0[0], ki0[1]); wk.y = cvtpk(ki0[2], ki0[3]); wk.z = cvtpk(ki1[0], ki1[1]); wk.w = cvtpk(ki1[2], ki1[3]);
;                 *(LAS u32x4*)(QIs + t * QK_LD + k0) = wq; *(LAS u32x4*)(KIs + t * QK_LD + k0) = wk;
;                 {
;                     const int w8 = k0 >> 5, u4 = (k0 & 31) >> 2;
;                     bf16* qf = QIg + ((((size_t)item * 8 + w8) * 4 + (t >> 4)) * 64 + (t & 15)) * 8;
;                     u32x2 a0; a0.x = wq.x; a0.y = wq.y; u32x2 a1; a1.x = wq.z; a1.y = wq.w;
;                     *(u32x2*)(qf + ((u4 & 3) * 16) * 8 + (u4 >> 2) * 4) = a0; *(u32x2*)(qf + (((u4 + 1) & 3) * 16) * 8 + ((u4 + 1) >> 2) * 4) = a1; }
;                 bf16* kt = KETg + (((((size_t)item * 8 + (k0 >> 5)) * 2 + ((k0 >> 4) & 1)) * 2 + (t >> 5)) * 64 + ((t >> 3) & 3) * 16 + (k0 & 15)) * 8 + (t & 7);
; #pragma unroll
.LBB0_829:
	s_or_b64 exec, exec, vcc
	v_mov_b32_e32 v43, s71
	v_or_b32_e32 v42, s70, v20
	v_lshlrev_b64 v[44:45], 10, v[42:43]
	v_or_b32_e32 v44, s69, v44
	v_lshl_add_u64 v[2:3], v[44:45], 0, s[28:29]
	v_lshlrev_b64 v[6:7], 1, v[2:3]
	v_lshl_add_u64 v[2:3], s[54:55], 0, v[6:7]
	v_lshl_add_u64 v[6:7], s[92:93], 0, v[6:7]
	s_waitcnt lgkmcnt(0)
	s_barrier
	v_mov_b32_e32 v2, v96
	v_mov_b32_e32 v3, v97
	v_mov_b32_e32 v4, v98
	v_mov_b32_e32 v5, v99
	v_mov_b32_e32 v70, s24
	v_mov_b32_e32 v6, v100
	v_mov_b32_e32 v7, v101
	v_mov_b32_e32 v8, v102
	v_mov_b32_e32 v9, v103
	s_ashr_i32 s69, s68, 31
	s_lshl_b64 s[70:71], s[68:69], 3
	s_add_u32 s90, s70, s25
	s_addc_u32 s91, s71, s27
	s_lshl_b64 s[90:91], s[90:91], 12
	v_lshlrev_b32_e32 v75, 16, v2
	v_and_b32_e32 v76, 0xffff0000, v2
	v_lshlrev_b32_e32 v77, 16, v3
	v_and_b32_e32 v73, 0xffff0000, v3
	v_lshlrev_b32_e32 v78, 16, v4
	v_and_b32_e32 v79, 0xffff0000, v4
	v_lshlrev_b32_e32 v80, 16, v5
	v_and_b32_e32 v74, 0xffff0000, v5
	v_lshlrev_b32_e32 v81, 16, v6
	v_and_b32_e32 v82, 0xffff0000, v6
	v_lshlrev_b32_e32 v83, 16, v7
	v_and_b32_e32 v72, 0xffff0000, v7
	v_lshlrev_b32_e32 v84, 16, v8
	v_and_b32_e32 v85, 0xffff0000, v8
	v_lshlrev_b32_e32 v86, 16, v9
	v_and_b32_e32 v71, 0xffff0000, v9
	ds_read_b128 v[6:9], v49
	ds_read_b128 v[2:5], v49 offset:16
	ds_read_b128 v[14:17], v70
	ds_read_b128 v[10:13], v70 offset:16
	s_waitcnt lgkmcnt(3)
	v_mul_f32_e32 v87, 0x3fb8aa3b, v6
	v_exp_f32_e32 v87, v87
	s_waitcnt lgkmcnt(2)
	v_mul_f32_e32 v88, 0x3fb8aa3b, v2
	v_exp_f32_e32 v88, v88
	v_mul_f32_e32 v75, v87, v75
	v_mul_f32_e32 v87, 0xbfb8aa3b, v6
	s_waitcnt lgkmcnt(1)
	v_sub_f32_e32 v6, v14, v6
	v_mul_f32_e32 v78, v88, v78
	v_mul_f32_e32 v88, 0xbfb8aa3b, v2
	v_mul_f32_e32 v6, 0x3fb8aa3b, v6
	s_waitcnt lgkmcnt(0)
	v_sub_f32_e32 v2, v10, v2
	v_exp_f32_e32 v6, v6
	v_mul_f32_e32 v2, 0x3fb8aa3b, v2
	v_exp_f32_e32 v2, v2
	v_exp_f32_e32 v87, v87
	v_mul_f32_e32 v14, v6, v81
	v_mul_f32_e32 v6, 0x3fb8aa3b, v3
	v_mul_f32_e32 v10, v2, v84
	v_mul_f32_e32 v2, 0x3fb8aa3b, v7
	v_exp_f32_e32 v6, v6
	v_exp_f32_e32 v2, v2
	v_exp_f32_e32 v88, v88
	v_mul_f32_e32 v87, v87, v81
	v_mul_f32_e32 v6, v6, v79
	v_mul_f32_e32 v79, 0xbfb8aa3b, v3
	v_sub_f32_e32 v3, v11, v3
	v_mul_f32_e32 v2, v2, v76
	v_mul_f32_e32 v76, 0xbfb8aa3b, v7
	v_sub_f32_e32 v7, v15, v7
	v_mul_f32_e32 v3, 0x3fb8aa3b, v3
	v_mul_f32_e32 v7, 0x3fb8aa3b, v7
	v_exp_f32_e32 v3, v3
	v_exp_f32_e32 v7, v7
	v_exp_f32_e32 v76, v76
	v_exp_f32_e32 v79, v79
	v_mul_f32_e32 v11, v3, v85
	v_mul_f32_e32 v3, 0x3fb8aa3b, v8
	v_mul_f32_e32 v15, v7, v82
	v_exp_f32_e32 v3, v3
	v_mul_f32_e32 v7, 0x3fb8aa3b, v4
	v_exp_f32_e32 v7, v7
	v_mul_f32_e32 v76, v76, v82
	v_mul_f32_e32 v3, v3, v77
	v_mul_f32_e32 v77, 0xbfb8aa3b, v8
	v_sub_f32_e32 v8, v16, v8
	v_mul_f32_e32 v7, v7, v80
	v_mul_f32_e32 v80, 0xbfb8aa3b, v4
	v_mul_f32_e32 v8, 0x3fb8aa3b, v8
	v_sub_f32_e32 v4, v12, v4
	v_exp_f32_e32 v8, v8
	v_mul_f32_e32 v4, 0x3fb8aa3b, v4
	v_exp_f32_e32 v4, v4
	v_exp_f32_e32 v77, v77
	v_mul_f32_e32 v16, v8, v83
	v_mul_f32_e32 v8, 0x3fb8aa3b, v5
	v_mul_f32_e32 v12, v4, v86
	v_mul_f32_e32 v4, 0x3fb8aa3b, v9
	v_exp_f32_e32 v8, v8
	v_exp_f32_e32 v4, v4
	v_exp_f32_e32 v80, v80
	v_mul_f32_e32 v77, v77, v83
	v_mul_f32_e32 v8, v8, v74
	v_mul_f32_e32 v74, 0xbfb8aa3b, v5
	v_sub_f32_e32 v5, v13, v5
	v_mul_f32_e32 v4, v4, v73
	v_mul_f32_e32 v73, 0xbfb8aa3b, v9
	v_sub_f32_e32 v9, v17, v9
	v_mul_f32_e32 v5, 0x3fb8aa3b, v5
	v_exp_f32_e32 v73, v73
	v_mul_f32_e32 v9, 0x3fb8aa3b, v9
	v_exp_f32_e32 v5, v5
	v_exp_f32_e32 v74, v74
	v_exp_f32_e32 v9, v9
	v_mul_f32_e32 v73, v73, v72
	v_mul_f32_e32 v13, v5, v71
	v_cvt_pk_bf16_f32 v2, v75, v2
	v_cvt_pk_bf16_f32 v3, v3, v4
	v_cvt_pk_bf16_f32 v4, v78, v6
	v_cvt_pk_bf16_f32 v5, v7, v8
	v_cvt_pk_bf16_f32 v6, v87, v76
	v_cvt_pk_bf16_f32 v7, v77, v73
	v_mul_f32_e32 v88, v88, v84
	v_mul_f32_e32 v79, v79, v85
	v_mul_f32_e32 v80, v80, v86
	v_mul_f32_e32 v74, v74, v71
	v_mul_f32_e32 v17, v9, v72
	v_cvt_pk_bf16_f32 v8, v88, v79
	v_cvt_pk_bf16_f32 v9, v80, v74
	ds_write_b128 v50, v[2:5]
	ds_write_b128 v51, v[6:9]
	v_lshl_add_u64 v[6:7], v[40:41], 0, s[90:91]
	global_store_dwordx2 v[6:7], v[2:3], off
	global_store_dwordx2 v[6:7], v[4:5], off offset:256
	v_or_b32_e32 v2, s90, v53
	v_mov_b32_e32 v3, s91
	v_lshl_add_u64 v[2:3], v[26:27], 0, v[2:3]
	v_cvt_pk_bf16_f32 v4, v14, v1
	global_store_short v[2:3], v4, off
	v_cvt_pk_bf16_f32 v4, v10, v1
	global_store_short v[2:3], v4, off offset:64
	v_cvt_pk_bf16_f32 v4, v15, v1
	global_store_short v[2:3], v4, off offset:16
	v_cvt_pk_bf16_f32 v4, v11, v1
	global_store_short v[2:3], v4, off offset:80
	v_cvt_pk_bf16_f32 v4, v16, v1
	global_store_short v[2:3], v4, off offset:32
	v_cvt_pk_bf16_f32 v4, v12, v1
	global_store_short v[2:3], v4, off offset:96
	v_cvt_pk_bf16_f32 v4, v17, v1
	global_store_short v[2:3], v4, off offset:48
	v_cvt_pk_bf16_f32 v4, v13, v1
	global_store_short v[2:3], v4, off offset:112
	v_lshl_add_u64 v[2:3], v[44:45], 0, s[58:59]
	v_lshlrev_b64 v[6:7], 1, v[2:3]
	v_lshl_add_u64 v[2:3], s[54:55], 0, v[6:7]
	v_lshl_add_u64 v[6:7], s[92:93], 0, v[6:7]
	v_mov_b32_e32 v2, v104
	v_mov_b32_e32 v3, v105
	v_mov_b32_e32 v4, v106
	v_mov_b32_e32 v5, v107
	s_add_u32 s90, s70, s35
	v_mov_b32_e32 v6, v108
	v_mov_b32_e32 v7, v109
	v_mov_b32_e32 v8, v110
	v_mov_b32_e32 v9, v111
	s_addc_u32 s91, s71, s37
	s_lshl_b64 s[90:91], s[90:91], 12
	v_lshlrev_b32_e32 v71, 16, v2
	v_and_b32_e32 v72, 0xffff0000, v2
	v_lshlrev_b32_e32 v73, 16, v3
	v_and_b32_e32 v74, 0xffff0000, v3
	v_lshlrev_b32_e32 v75, 16, v4
	v_and_b32_e32 v76, 0xffff0000, v4
	v_lshlrev_b32_e32 v77, 16, v5
	v_and_b32_e32 v78, 0xffff0000, v5
	v_lshlrev_b32_e32 v79, 16, v6
	v_and_b32_e32 v80, 0xffff0000, v6
	v_lshlrev_b32_e32 v81, 16, v7
	v_and_b32_e32 v82, 0xffff0000, v7
	v_lshlrev_b32_e32 v83, 16, v8
	v_and_b32_e32 v84, 0xffff0000, v8
	v_lshlrev_b32_e32 v85, 16, v9
	v_and_b32_e32 v86, 0xffff0000, v9
	ds_read_b128 v[10:13], v49 offset:256
	ds_read_b128 v[2:5], v49 offset:272
	ds_read_b128 v[14:17], v70 offset:256
	ds_read_b128 v[6:9], v70 offset:272
	s_waitcnt lgkmcnt(3)
; #define LAS __attribute__((address_space(3)))
; __device__ __forceinline__ void phase_gla_prep(KArgs a, LAS unsigned char* lds, int tid, int wave, int lane) {
;     ...
;             for (int i = 0; i < 4; ++i) { const int kg = wave + 8 * i, k0 = kg * 8; const size_t src = (row0 + t) * 1024 + h * 256 + k0;
;                 const u32x4 qw = *(const u32x4*)(Q + src), kw = *(const u32x4*)(Kf + src);
;                 const f32x4 q0 = (f32x4){bflo(qw.x), bfhi(qw.x), bflo(qw.y), bfhi(qw.y)}, q1 = (f32x4){bflo(qw.z), bfhi(qw.z), bflo(qw.w), bfhi(qw.w)}, c0 = (f32x4){bflo(kw.x), bfhi(kw.x), bflo(kw.y), bfhi(kw.y)}, c1 = (f32x4){bflo(kw.z), bfhi(kw.z), bflo(kw.w), bfhi(kw.w)};
;                 const f32x4 b0 = *(const LAS f32x4*)(BC + t * BC_LD + k0), b1 = *(const LAS f32x4*)(BC + t * BC_LD + k0 + 4), l0 = *(const LAS f32x4*)(BC + 63 * BC_LD + k0), l1 = *(const LAS f32x4*)(BC + 63 * BC_LD + k0 + 4);
;                 f32x4 qi0, qi1, ki0, ki1, ke0, ke1;
; #pragma unroll
;                 for (int e = 0; e < 4; ++e) { const float ep0 = __expf(b0[e]), ep1 = __expf(b1[e]);
;                     qi0[e] = q0[e] * ep0; qi1[e] = q1[e] * ep1; ki0[e] = c0[e] * __expf(-b0[e]); ki1[e] = c1[e] * __expf(-b1[e]);
;                     ke0[e] = c0[e] * __expf(l0[e] - b0[e]); ke1[e] = c1[e] * __expf(l1[e] - b1[e]); }
;                 u32x4 wq; wq.x = cvtpk(qi0[0], qi0[1]); wq.y = cvtpk(qi0[2], qi0[3]); wq.z = cvtpk(qi1[0], qi1[1]); wq.w = cvtpk(qi1[2], qi1[3]);
;                 u32x4 wk; wk.x = cvtpk(ki0[0], ki0[1]); wk.y = cvtpk(ki0[2], ki0[3]); wk.z = cvtpk(ki1[0], ki1[1]); wk.w = cvtpk(ki1[2], ki1[3]);
;                 *(LAS u32x4*)(QIs + t * QK_LD + k0) = wq; *(LAS u32x4*)(KIs + t * QK_LD + k0) = wk;
;                 {
;                     const int w8 = k0 >> 5, u4 = (k0 & 31) >> 2;
;                     bf16* qf = QIg + ((((size_t)item * 8 + w8) * 4 + (t >> 4)) * 64 + (t & 15)) * 8;
;                     u32x2 a0; a0.x = wq.x; a0.y = wq.y; u32x2 a1; a1.x = wq.z; a1.y = wq.w;
;                     *(u32x2*)(qf + ((u4 & 3) * 16) * 8 + (u4 >> 2) * 4) = a0; *(u32x2*)(qf + (((u4 + 1) & 3) * 16) * 8 + ((u4 + 1) >> 2) * 4) = a1; }
;                 bf16* kt = KETg + (((((size_t)item * 8 + (k0 >> 5)) * 2 + ((k0 >> 4) & 1)) * 2 + (t >> 5)) * 64 + ((t >> 3) & 3) * 16 + (k0 & 15)) * 8 + (t & 7);
; #pragma unroll
	v_mul_f32_e32 v87, 0x3fb8aa3b, v10
	s_waitcnt lgkmcnt(2)
	v_mul_f32_e32 v88, 0x3fb8aa3b, v2
	v_exp_f32_e32 v88, v88
	v_exp_f32_e32 v87, v87
	v_mul_f32_e32 v75, v88, v75
	v_mul_f32_e32 v88, 0xbfb8aa3b, v2
	s_waitcnt lgkmcnt(0)
	v_sub_f32_e32 v2, v6, v2
	v_mul_f32_e32 v6, 0x3fb8aa3b, v3
	v_mul_f32_e32 v2, 0x3fb8aa3b, v2
	v_exp_f32_e32 v6, v6
	v_exp_f32_e32 v2, v2
	v_mul_f32_e32 v71, v87, v71
	v_mul_f32_e32 v87, 0xbfb8aa3b, v10
	v_mul_f32_e32 v6, v6, v76
	v_mul_f32_e32 v76, 0xbfb8aa3b, v3
	v_sub_f32_e32 v3, v7, v3
	v_mul_f32_e32 v7, 0x3fb8aa3b, v4
	v_sub_f32_e32 v10, v14, v10
	v_mul_f32_e32 v14, v2, v83
	v_mul_f32_e32 v2, 0x3fb8aa3b, v11
	v_mul_f32_e32 v3, 0x3fb8aa3b, v3
	v_exp_f32_e32 v7, v7
	v_exp_f32_e32 v2, v2
	v_exp_f32_e32 v3, v3
	v_exp_f32_e32 v87, v87
	v_mul_f32_e32 v7, v7, v77
	v_mul_f32_e32 v77, 0xbfb8aa3b, v4
	v_sub_f32_e32 v4, v8, v4
	v_mul_f32_e32 v2, v2, v72
	v_mul_f32_e32 v72, 0xbfb8aa3b, v11
	v_sub_f32_e32 v11, v15, v11
	v_mul_f32_e32 v15, v3, v84
	v_mul_f32_e32 v3, 0x3fb8aa3b, v12
	v_mul_f32_e32 v4, 0x3fb8aa3b, v4
	v_exp_f32_e32 v3, v3
	v_exp_f32_e32 v4, v4
	v_mul_f32_e32 v8, 0x3fb8aa3b, v5
	v_exp_f32_e32 v8, v8
	v_mul_f32_e32 v3, v3, v73
	v_mul_f32_e32 v73, 0xbfb8aa3b, v12
	v_sub_f32_e32 v12, v16, v12
	v_mul_f32_e32 v16, v4, v85
	v_mul_f32_e32 v4, 0x3fb8aa3b, v13
	v_exp_f32_e32 v4, v4
	v_mul_f32_e32 v8, v8, v78
	v_mul_f32_e32 v78, 0xbfb8aa3b, v5
	v_sub_f32_e32 v5, v9, v5
	v_mul_f32_e32 v4, v4, v74
	v_mul_f32_e32 v74, 0xbfb8aa3b, v13
	v_mul_f32_e32 v5, 0x3fb8aa3b, v5
	v_exp_f32_e32 v72, v72
	v_exp_f32_e32 v73, v73
	v_exp_f32_e32 v74, v74
	v_exp_f32_e32 v5, v5
	v_exp_f32_e32 v88, v88
	v_exp_f32_e32 v76, v76
	v_exp_f32_e32 v77, v77
	v_exp_f32_e32 v78, v78
	v_mul_f32_e32 v10, 0x3fb8aa3b, v10
	v_exp_f32_e32 v10, v10
	v_mul_f32_e32 v87, v87, v79
	v_mul_f32_e32 v72, v72, v80
	v_mul_f32_e32 v11, 0x3fb8aa3b, v11
	v_mul_f32_e32 v73, v73, v81
	v_mul_f32_e32 v74, v74, v82
	v_sub_f32_e32 v13, v17, v13
	v_mul_f32_e32 v17, v5, v86
	v_cvt_pk_bf16_f32 v2, v71, v2
	v_cvt_pk_bf16_f32 v3, v3, v4
	v_cvt_pk_bf16_f32 v4, v75, v6
	v_cvt_pk_bf16_f32 v5, v7, v8
	v_cvt_pk_bf16_f32 v6, v87, v72
	v_cvt_pk_bf16_f32 v7, v73, v74
	v_mul_f32_e32 v88, v88, v83
	v_mul_f32_e32 v76, v76, v84
	v_exp_f32_e32 v11, v11
	v_mul_f32_e32 v77, v77, v85
	v_mul_f32_e32 v78, v78, v86
	v_cvt_pk_bf16_f32 v8, v88, v76
	v_cvt_pk_bf16_f32 v9, v77, v78
	ds_write_b128 v50, v[2:5] offset:128
	ds_write_b128 v51, v[6:9] offset:128
	v_lshl_add_u64 v[6:7], v[40:41], 0, s[90:91]
	v_mul_f32_e32 v12, 0x3fb8aa3b, v12
	global_store_dwordx2 v[6:7], v[2:3], off
	global_store_dwordx2 v[6:7], v[4:5], off offset:256
	v_or_b32_e32 v2, s90, v53
	v_mov_b32_e32 v3, s91
	v_mul_f32_e32 v10, v10, v79
	v_exp_f32_e32 v12, v12
	v_lshl_add_u64 v[2:3], v[26:27], 0, v[2:3]
	v_cvt_pk_bf16_f32 v4, v10, v1
	v_mul_f32_e32 v13, 0x3fb8aa3b, v13
	global_store_short v[2:3], v4, off
	v_cvt_pk_bf16_f32 v4, v14, v1
	v_mul_f32_e32 v11, v11, v80
	v_exp_f32_e32 v13, v13
	global_store_short v[2:3], v4, off offset:64
	v_cvt_pk_bf16_f32 v4, v11, v1
	global_store_short v[2:3], v4, off offset:16
	v_cvt_pk_bf16_f32 v4, v15, v1
	v_mul_f32_e32 v12, v12, v81
	global_store_short v[2:3], v4, off offset:80
	v_cvt_pk_bf16_f32 v4, v12, v1
	global_store_short v[2:3], v4, off offset:32
	v_cvt_pk_bf16_f32 v4, v16, v1
	v_mul_f32_e32 v13, v13, v82
	global_store_short v[2:3], v4, off offset:96
	v_cvt_pk_bf16_f32 v4, v13, v1
	global_store_short v[2:3], v4, off offset:48
	v_cvt_pk_bf16_f32 v4, v17, v1
	global_store_short v[2:3], v4, off offset:112
	v_lshl_add_u64 v[2:3], v[44:45], 0, s[78:79]
	v_lshlrev_b64 v[6:7], 1, v[2:3]
	v_lshl_add_u64 v[2:3], s[54:55], 0, v[6:7]
	v_lshl_add_u64 v[6:7], s[92:93], 0, v[6:7]
	v_mov_b32_e32 v2, v112
	v_mov_b32_e32 v3, v113
	v_mov_b32_e32 v4, v114
	v_mov_b32_e32 v5, v115
	s_add_u32 s90, s70, s40
	v_mov_b32_e32 v6, v116
	v_mov_b32_e32 v7, v117
	v_mov_b32_e32 v8, v118
	v_mov_b32_e32 v9, v119
	s_addc_u32 s91, s71, s45
	s_lshl_b64 s[90:91], s[90:91], 12
	s_add_u32 s70, s70, s47
	s_addc_u32 s71, s71, s56
	s_lshl_b64 s[70:71], s[70:71], 12
	v_lshlrev_b32_e32 v71, 16, v2
	v_and_b32_e32 v72, 0xffff0000, v2
	v_lshlrev_b32_e32 v73, 16, v3
	v_and_b32_e32 v74, 0xffff0000, v3
	v_lshlrev_b32_e32 v75, 16, v4
	v_and_b32_e32 v76, 0xffff0000, v4
	v_lshlrev_b32_e32 v77, 16, v5
	v_and_b32_e32 v78, 0xffff0000, v5
	v_lshlrev_b32_e32 v79, 16, v6
	v_and_b32_e32 v80, 0xffff0000, v6
	v_lshlrev_b32_e32 v81, 16, v7
	v_and_b32_e32 v82, 0xffff0000, v7
	v_lshlrev_b32_e32 v83, 16, v8
	v_and_b32_e32 v84, 0xffff0000, v8
	v_lshlrev_b32_e32 v85, 16, v9
	v_and_b32_e32 v86, 0xffff0000, v9
	ds_read_b128 v[2:5], v49 offset:512
	ds_read_b128 v[6:9], v49 offset:528
	ds_read_b128 v[10:13], v70 offset:512
	ds_read_b128 v[14:17], v70 offset:528
	s_waitcnt lgkmcnt(3)
	v_mul_f32_e32 v87, 0x3fb8aa3b, v2
	v_exp_f32_e32 v87, v87
	s_waitcnt lgkmcnt(2)
	v_mul_f32_e32 v88, 0x3fb8aa3b, v6
	v_exp_f32_e32 v88, v88
	v_mul_f32_e32 v71, v87, v71
	v_mul_f32_e32 v87, 0xbfb8aa3b, v2
	s_waitcnt lgkmcnt(1)
	v_sub_f32_e32 v2, v10, v2
	v_mul_f32_e32 v2, 0x3fb8aa3b, v2
	v_exp_f32_e32 v2, v2
	v_mul_f32_e32 v75, v88, v75
	v_mul_f32_e32 v88, 0xbfb8aa3b, v6
	v_exp_f32_e32 v87, v87
	v_mul_f32_e32 v10, v2, v79
	s_waitcnt lgkmcnt(0)
; #define LAS __attribute__((address_space(3)))
; __device__ __forceinline__ void phase_gla_prep(KArgs a, LAS unsigned char* lds, int tid, int wave, int lane) {
;     ...
;             for (int i = 0; i < 4; ++i) { const int kg = wave + 8 * i, k0 = kg * 8; const size_t src = (row0 + t) * 1024 + h * 256 + k0;
;                 const u32x4 qw = *(const u32x4*)(Q + src), kw = *(const u32x4*)(Kf + src);
;                 const f32x4 q0 = (f32x4){bflo(qw.x), bfhi(qw.x), bflo(qw.y), bfhi(qw.y)}, q1 = (f32x4){bflo(qw.z), bfhi(qw.z), bflo(qw.w), bfhi(qw.w)}, c0 = (f32x4){bflo(kw.x), bfhi(kw.x), bflo(kw.y), bfhi(kw.y)}, c1 = (f32x4){bflo(kw.z), bfhi(kw.z), bflo(kw.w), bfhi(kw.w)};
;                 const f32x4 b0 = *(const LAS f32x4*)(BC + t * BC_LD + k0), b1 = *(const LAS f32x4*)(BC + t * BC_LD + k0 + 4), l0 = *(const LAS f32x4*)(BC + 63 * BC_LD + k0), l1 = *(const LAS f32x4*)(BC + 63 * BC_LD + k0 + 4);
;                 f32x4 qi0, qi1, ki0, ki1, ke0, ke1;
; #pragma unroll
;                 for (int e = 0; e < 4; ++e) { const float ep0 = __expf(b0[e]), ep1 = __expf(b1[e]);
;                     qi0[e] = q0[e] * ep0; qi1[e] = q1[e] * ep1; ki0[e] = c0[e] * __expf(-b0[e]); ki1[e] = c1[e] * __expf(-b1[e]);
;                     ke0[e] = c0[e] * __expf(l0[e] - b0[e]); ke1[e] = c1[e] * __expf(l1[e] - b1[e]); }
;                 u32x4 wq; wq.x = cvtpk(qi0[0], qi0[1]); wq.y = cvtpk(qi0[2], qi0[3]); wq.z = cvtpk(qi1[0], qi1[1]); wq.w = cvtpk(qi1[2], qi1[3]);
;                 u32x4 wk; wk.x = cvtpk(ki0[0], ki0[1]); wk.y = cvtpk(ki0[2], ki0[3]); wk.z = cvtpk(ki1[0], ki1[1]); wk.w = cvtpk(ki1[2], ki1[3]);
;                 *(LAS u32x4*)(QIs + t * QK_LD + k0) = wq; *(LAS u32x4*)(KIs + t * QK_LD + k0) = wk;
;                 {
;                     const int w8 = k0 >> 5, u4 = (k0 & 31) >> 2;
;                     bf16* qf = QIg + ((((size_t)item * 8 + w8) * 4 + (t >> 4)) * 64 + (t & 15)) * 8;
;                     u32x2 a0; a0.x = wq.x; a0.y = wq.y; u32x2 a1; a1.x = wq.z; a1.y = wq.w;
;                     *(u32x2*)(qf + ((u4 & 3) * 16) * 8 + (u4 >> 2) * 4) = a0; *(u32x2*)(qf + (((u4 + 1) & 3) * 16) * 8 + ((u4 + 1) >> 2) * 4) = a1; }
;                 bf16* kt = KETg + (((((size_t)item * 8 + (k0 >> 5)) * 2 + ((k0 >> 4) & 1)) * 2 + (t >> 5)) * 64 + ((t >> 3) & 3) * 16 + (k0 & 15)) * 8 + (t & 7);
; #pragma unroll
	v_sub_f32_e32 v2, v14, v6
	v_mul_f32_e32 v2, 0x3fb8aa3b, v2
	v_exp_f32_e32 v2, v2
	v_mul_f32_e32 v6, 0x3fb8aa3b, v7
	v_exp_f32_e32 v6, v6
	v_exp_f32_e32 v88, v88
	v_mul_f32_e32 v14, v2, v83
	v_mul_f32_e32 v2, 0x3fb8aa3b, v3
	v_exp_f32_e32 v2, v2
	v_mul_f32_e32 v6, v6, v76
	v_mul_f32_e32 v76, 0xbfb8aa3b, v7
	v_exp_f32_e32 v76, v76
	v_mul_f32_e32 v2, v2, v72
	v_mul_f32_e32 v72, 0xbfb8aa3b, v3
	v_sub_f32_e32 v3, v11, v3
	v_mul_f32_e32 v3, 0x3fb8aa3b, v3
	v_exp_f32_e32 v3, v3
	v_exp_f32_e32 v72, v72
	v_mul_f32_e32 v87, v87, v79
	v_cvt_pk_bf16_f32 v2, v71, v2
	v_mul_f32_e32 v11, v3, v80
	v_sub_f32_e32 v3, v15, v7
	v_mul_f32_e32 v3, 0x3fb8aa3b, v3
	v_exp_f32_e32 v3, v3
	v_mul_f32_e32 v7, 0x3fb8aa3b, v8
	v_exp_f32_e32 v7, v7
	v_mul_f32_e32 v72, v72, v80
	v_mul_f32_e32 v15, v3, v84
	v_mul_f32_e32 v3, 0x3fb8aa3b, v4
	v_exp_f32_e32 v3, v3
	v_mul_f32_e32 v7, v7, v77
	v_mul_f32_e32 v77, 0xbfb8aa3b, v8
	v_exp_f32_e32 v77, v77
	v_mul_f32_e32 v3, v3, v73
	v_mul_f32_e32 v73, 0xbfb8aa3b, v4
	v_sub_f32_e32 v4, v12, v4
	v_mul_f32_e32 v4, 0x3fb8aa3b, v4
	v_exp_f32_e32 v4, v4
	v_exp_f32_e32 v73, v73
	v_mul_f32_e32 v88, v88, v83
	v_mul_f32_e32 v76, v76, v84
	v_mul_f32_e32 v12, v4, v81
	v_sub_f32_e32 v4, v16, v8
	v_mul_f32_e32 v4, 0x3fb8aa3b, v4
	v_exp_f32_e32 v4, v4
	v_mul_f32_e32 v8, 0x3fb8aa3b, v9
	v_exp_f32_e32 v8, v8
	v_mul_f32_e32 v73, v73, v81
	v_mul_f32_e32 v16, v4, v85
	v_mul_f32_e32 v4, 0x3fb8aa3b, v5
	v_exp_f32_e32 v4, v4
	v_mul_f32_e32 v8, v8, v78
	v_mul_f32_e32 v78, 0xbfb8aa3b, v9
	v_exp_f32_e32 v78, v78
	v_mul_f32_e32 v4, v4, v74
	v_mul_f32_e32 v74, 0xbfb8aa3b, v5
	v_sub_f32_e32 v5, v13, v5
	v_mul_f32_e32 v5, 0x3fb8aa3b, v5
	v_exp_f32_e32 v5, v5
	v_exp_f32_e32 v74, v74
	v_cvt_pk_bf16_f32 v3, v3, v4
	v_cvt_pk_bf16_f32 v4, v75, v6
	v_mul_f32_e32 v13, v5, v82
	v_sub_f32_e32 v5, v17, v9
	v_mul_f32_e32 v5, 0x3fb8aa3b, v5
	v_exp_f32_e32 v5, v5
	v_mul_f32_e32 v74, v74, v82
	v_mul_f32_e32 v77, v77, v85
	v_mul_f32_e32 v78, v78, v86
	v_mul_f32_e32 v17, v5, v86
	v_cvt_pk_bf16_f32 v5, v7, v8
	v_cvt_pk_bf16_f32 v6, v87, v72
	v_cvt_pk_bf16_f32 v7, v73, v74
	v_cvt_pk_bf16_f32 v8, v88, v76
	v_cvt_pk_bf16_f32 v9, v77, v78
	ds_write_b128 v50, v[2:5] offset:256
	ds_write_b128 v51, v[6:9] offset:256
	v_lshl_add_u64 v[6:7], v[40:41], 0, s[90:91]
	global_store_dwordx2 v[6:7], v[2:3], off
	global_store_dwordx2 v[6:7], v[4:5], off offset:256
	v_or_b32_e32 v2, s90, v53
	v_mov_b32_e32 v3, s91
	v_lshl_add_u64 v[2:3], v[26:27], 0, v[2:3]
	v_cvt_pk_bf16_f32 v4, v10, v1
	global_store_short v[2:3], v4, off
	v_cvt_pk_bf16_f32 v4, v14, v1
	global_store_short v[2:3], v4, off offset:64
	v_cvt_pk_bf16_f32 v4, v11, v1
	global_store_short v[2:3], v4, off offset:16
	v_cvt_pk_bf16_f32 v4, v15, v1
	global_store_short v[2:3], v4, off offset:80
	v_cvt_pk_bf16_f32 v4, v12, v1
	global_store_short v[2:3], v4, off offset:32
	v_cvt_pk_bf16_f32 v4, v16, v1
	global_store_short v[2:3], v4, off offset:96
	v_cvt_pk_bf16_f32 v4, v13, v1
	global_store_short v[2:3], v4, off offset:48
	v_cvt_pk_bf16_f32 v4, v17, v1
	global_store_short v[2:3], v4, off offset:112
	v_lshl_add_u64 v[2:3], v[44:45], 0, s[82:83]
	v_lshlrev_b64 v[6:7], 1, v[2:3]
	v_lshl_add_u64 v[2:3], s[54:55], 0, v[6:7]
	v_lshl_add_u64 v[6:7], s[92:93], 0, v[6:7]
	v_mov_b32_e32 v2, v120
	v_mov_b32_e32 v3, v121
	v_mov_b32_e32 v4, v122
	v_mov_b32_e32 v5, v123
	s_nop 0
	v_mov_b32_e32 v6, v124
	v_mov_b32_e32 v7, v125
	v_mov_b32_e32 v8, v126
	v_mov_b32_e32 v9, v127
	v_lshlrev_b32_e32 v44, 16, v2
	v_and_b32_e32 v45, 0xffff0000, v2
	v_lshlrev_b32_e32 v71, 16, v3
	v_and_b32_e32 v72, 0xffff0000, v3
	v_lshlrev_b32_e32 v73, 16, v4
	v_and_b32_e32 v74, 0xffff0000, v4
	v_lshlrev_b32_e32 v75, 16, v5
	v_and_b32_e32 v76, 0xffff0000, v5
	v_lshlrev_b32_e32 v77, 16, v6
	v_and_b32_e32 v78, 0xffff0000, v6
	v_lshlrev_b32_e32 v79, 16, v7
	v_and_b32_e32 v80, 0xffff0000, v7
	v_lshlrev_b32_e32 v81, 16, v8
	v_and_b32_e32 v82, 0xffff0000, v8
	v_lshlrev_b32_e32 v83, 16, v9
	v_and_b32_e32 v84, 0xffff0000, v9
	ds_read_b128 v[2:5], v49 offset:768
	ds_read_b128 v[6:9], v49 offset:784
	ds_read_b128 v[10:13], v70 offset:768
	ds_read_b128 v[14:17], v70 offset:784
	s_waitcnt lgkmcnt(3)
; #define LAS __attribute__((address_space(3)))
; __device__ __forceinline__ unsigned cvtpk(float lo, float hi) { unsigned r; asm volatile("v_cvt_pk_bf16_f32 %0, %1, %2" : "=v"(r) : "v"(lo), "v"(hi)); return r; }
; __device__ __forceinline__ void phase_gla_prep(KArgs a, LAS unsigned char* lds, int tid, int wave, int lane) {
;     ...
;                 for (int e = 0; e < 4; ++e) { const float ep0 = __expf(b0[e]), ep1 = __expf(b1[e]);
;                     qi0[e] = q0[e] * ep0; qi1[e] = q1[e] * ep1; ki0[e] = c0[e] * __expf(-b0[e]); ki1[e] = c1[e] * __expf(-b1[e]);
;                     ke0[e] = c0[e] * __expf(l0[e] - b0[e]); ke1[e] = c1[e] * __expf(l1[e] - b1[e]); }
;                 u32x4 wq; wq.x = cvtpk(qi0[0], qi0[1]); wq.y = cvtpk(qi0[2], qi0[3]); wq.z = cvtpk(qi1[0], qi1[1]); wq.w = cvtpk(qi1[2], qi1[3]);
;                 u32x4 wk; wk.x = cvtpk(ki0[0], ki0[1]); wk.y = cvtpk(ki0[2], ki0[3]); wk.z = cvtpk(ki1[0], ki1[1]); wk.w = cvtpk(ki1[2], ki1[3]);
;                 *(LAS u32x4*)(QIs + t * QK_LD + k0) = wq; *(LAS u32x4*)(KIs + t * QK_LD + k0) = wk;
;                 {
;                     const int w8 = k0 >> 5, u4 = (k0 & 31) >> 2;
;                     bf16* qf = QIg + ((((size_t)item * 8 + w8) * 4 + (t >> 4)) * 64 + (t & 15)) * 8;
;                     u32x2 a0; a0.x = wq.x; a0.y = wq.y; u32x2 a1; a1.x = wq.z; a1.y = wq.w;
;                     *(u32x2*)(qf + ((u4 & 3) * 16) * 8 + (u4 >> 2) * 4) = a0; *(u32x2*)(qf + (((u4 + 1) & 3) * 16) * 8 + ((u4 + 1) >> 2) * 4) = a1; }
;                 bf16* kt = KETg + (((((size_t)item * 8 + (k0 >> 5)) * 2 + ((k0 >> 4) & 1)) * 2 + (t >> 5)) * 64 + ((t >> 3) & 3) * 16 + (k0 & 15)) * 8 + (t & 7);
; #pragma unroll
;                 for (int e = 0; e < 4; ++e) { kt[(size_t)e * 8] = (bf16)(cvtpk(ke0[e], 0.f) & 0xffffu); kt[(size_t)(e + 4) * 8] = (bf16)(cvtpk(ke1[e], 0.f) & 0xffffu); }
;             }
;             if (tid < 256) DECg[(size_t)item * 256 + tid] = __expf(BC[63 * BC_LD + tid]);
	v_mul_f32_e32 v70, 0x3fb8aa3b, v2
	s_waitcnt lgkmcnt(2)
	v_mul_f32_e32 v85, 0x3fb8aa3b, v6
	v_exp_f32_e32 v70, v70
	v_exp_f32_e32 v85, v85
	v_mul_f32_e32 v44, v70, v44
	v_mul_f32_e32 v70, v85, v73
	v_mul_f32_e32 v73, 0xbfb8aa3b, v2
	s_waitcnt lgkmcnt(1)
	v_sub_f32_e32 v2, v10, v2
	v_mul_f32_e32 v2, 0x3fb8aa3b, v2
	v_exp_f32_e32 v2, v2
	v_mul_f32_e32 v85, 0xbfb8aa3b, v6
	v_exp_f32_e32 v73, v73
	v_exp_f32_e32 v85, v85
	v_mul_f32_e32 v10, v2, v77
	s_waitcnt lgkmcnt(0)
	v_sub_f32_e32 v2, v14, v6
	v_mul_f32_e32 v2, 0x3fb8aa3b, v2
	v_exp_f32_e32 v2, v2
	v_mul_f32_e32 v6, 0x3fb8aa3b, v7
	v_exp_f32_e32 v6, v6
	v_mul_f32_e32 v73, v73, v77
	v_mul_f32_e32 v14, v2, v81
	v_mul_f32_e32 v2, 0x3fb8aa3b, v3
	v_exp_f32_e32 v2, v2
	v_mul_f32_e32 v6, v6, v74
	v_mul_f32_e32 v74, 0xbfb8aa3b, v7
	v_exp_f32_e32 v74, v74
	v_mul_f32_e32 v2, v2, v45
	v_mul_f32_e32 v45, 0xbfb8aa3b, v3
	v_sub_f32_e32 v3, v11, v3
	v_mul_f32_e32 v3, 0x3fb8aa3b, v3
	v_exp_f32_e32 v3, v3
	v_exp_f32_e32 v45, v45
	v_cvt_pk_bf16_f32 v2, v44, v2
	v_mul_f32_e32 v85, v85, v81
	v_mul_f32_e32 v11, v3, v78
	v_sub_f32_e32 v3, v15, v7
	v_mul_f32_e32 v3, 0x3fb8aa3b, v3
	v_exp_f32_e32 v3, v3
	v_mul_f32_e32 v7, 0x3fb8aa3b, v8
	v_exp_f32_e32 v7, v7
	v_mul_f32_e32 v45, v45, v78
	v_mul_f32_e32 v15, v3, v82
	v_mul_f32_e32 v3, 0x3fb8aa3b, v4
	v_exp_f32_e32 v3, v3
	v_mul_f32_e32 v7, v7, v75
	v_mul_f32_e32 v75, 0xbfb8aa3b, v8
	v_exp_f32_e32 v75, v75
	v_mul_f32_e32 v3, v3, v71
	v_mul_f32_e32 v71, 0xbfb8aa3b, v4
	v_sub_f32_e32 v4, v12, v4
	v_mul_f32_e32 v4, 0x3fb8aa3b, v4
	v_exp_f32_e32 v4, v4
	v_exp_f32_e32 v71, v71
	v_mul_f32_e32 v74, v74, v82
	v_mul_f32_e32 v75, v75, v83
	v_mul_f32_e32 v12, v4, v79
	v_sub_f32_e32 v4, v16, v8
	v_mul_f32_e32 v4, 0x3fb8aa3b, v4
	v_exp_f32_e32 v4, v4
	v_mul_f32_e32 v8, 0x3fb8aa3b, v9
	v_exp_f32_e32 v8, v8
	v_mul_f32_e32 v71, v71, v79
	v_mul_f32_e32 v16, v4, v83
	v_mul_f32_e32 v4, 0x3fb8aa3b, v5
	v_exp_f32_e32 v4, v4
	v_mul_f32_e32 v8, v8, v76
	v_mul_f32_e32 v76, 0xbfb8aa3b, v9
	v_exp_f32_e32 v76, v76
	v_mul_f32_e32 v4, v4, v72
	v_mul_f32_e32 v72, 0xbfb8aa3b, v5
	v_sub_f32_e32 v5, v13, v5
	v_mul_f32_e32 v5, 0x3fb8aa3b, v5
	v_exp_f32_e32 v5, v5
	v_exp_f32_e32 v72, v72
	v_cvt_pk_bf16_f32 v3, v3, v4
	v_cvt_pk_bf16_f32 v4, v70, v6
	v_mul_f32_e32 v13, v5, v80
	v_sub_f32_e32 v5, v17, v9
	v_mul_f32_e32 v5, 0x3fb8aa3b, v5
	v_exp_f32_e32 v5, v5
	v_mul_f32_e32 v72, v72, v80
	v_mul_f32_e32 v76, v76, v84
	v_mul_f32_e32 v17, v5, v84
	v_cvt_pk_bf16_f32 v5, v7, v8
	v_cvt_pk_bf16_f32 v6, v73, v45
	v_cvt_pk_bf16_f32 v7, v71, v72
	v_cvt_pk_bf16_f32 v8, v85, v74
	v_cvt_pk_bf16_f32 v9, v75, v76
	ds_write_b128 v50, v[2:5] offset:384
	ds_write_b128 v51, v[6:9] offset:384
	v_lshl_add_u64 v[6:7], v[40:41], 0, s[70:71]
	global_store_dwordx2 v[6:7], v[2:3], off
	global_store_dwordx2 v[6:7], v[4:5], off offset:256
	v_or_b32_e32 v2, s70, v53
	v_mov_b32_e32 v3, s71
	v_lshl_add_u64 v[2:3], v[26:27], 0, v[2:3]
	v_cvt_pk_bf16_f32 v4, v10, v1
	global_store_short v[2:3], v4, off
	v_cvt_pk_bf16_f32 v4, v14, v1
	global_store_short v[2:3], v4, off offset:64
	v_cvt_pk_bf16_f32 v4, v11, v1
	global_store_short v[2:3], v4, off offset:16
	v_cvt_pk_bf16_f32 v4, v15, v1
	global_store_short v[2:3], v4, off offset:80
	v_cvt_pk_bf16_f32 v4, v12, v1
	global_store_short v[2:3], v4, off offset:32
	v_cvt_pk_bf16_f32 v4, v16, v1
	global_store_short v[2:3], v4, off offset:96
	v_cvt_pk_bf16_f32 v4, v13, v1
	global_store_short v[2:3], v4, off offset:48
	v_cvt_pk_bf16_f32 v4, v17, v1
	global_store_short v[2:3], v4, off offset:112
	s_and_saveexec_b64 s[70:71], s[4:5]
	s_cbranch_execz .LBB0_831
	ds_read_b32 v2, v19 offset:65520
	s_lshl_b64 s[90:91], s[68:69], 10
	s_waitcnt lgkmcnt(0)
	v_mul_f32_e32 v2, 0x3fb8aa3b, v2
	v_exp_f32_e32 v4, v2
	v_lshl_add_u64 v[2:3], v[28:29], 0, s[90:91]
	global_store_dword v[2:3], v4, off

; __device__ __forceinline__ void phase_gla_norm(KArgs a, int gw, int NGW, int lane) {
;     ...
;     for (int it = MPROMPT * 4 + gw; it < MREAL * 4; it += NGW) {
;         const int row = it >> 2, h = it & 3; const size_t off = (size_t)row * DM + h * 512 + lane * 4;
;         f32x4 o0, o1;
;         if (row < MPROMPT) { o0 = *(const f32x4*)(O + off); o1 = *(const f32x4*)(O + off + 256); }
;         else { const int s = row - MPROMPT; const u32x2 qw = *(const u32x2*)(Q + (size_t)row * 1024 + h * 256 + lane * 4), kw = *(const u32x2*)(Kf + (size_t)row * 1024 + h * 256 + lane * 4); const f32x4 q = (f32x4){bflo(qw.x), bfhi(qw.x), bflo(qw.y), bfhi(qw.y)}, k = (f32x4){bflo(kw.x), bfhi(kw.x), bflo(kw.y), bfhi(kw.y)};
;             const float qk = wave_sum((q[0] * k[0] + q[1] * k[1]) + (q[2] * k[2] + q[3] * k[3]));
;             const u32x2 va = *(const u32x2*)(V + off), vb = *(const u32x2*)(V + off + 256);
;             o0 = (f32x4){bflo(va.x), bfhi(va.x), bflo(va.y), bfhi(va.y)} * qk; o1 = (f32x4){bflo(vb.x), bfhi(vb.x), bflo(vb.y), bfhi(vb.y)} * qk;
; #pragma unroll
;             for (int p = 0; p < 8; ++p) { const float* op = OP + ((size_t)p * MSAMP + s) * DM + h * 512 + lane * 4; o0 = o0 + *(const f32x4*)op; o1 = o1 + *(const f32x4*)(op + 256); } }
.LBB0_971:
	s_ashr_i32 s14, s2, 2
	s_ashr_i32 s15, s14, 31
	s_lshl_b64 s[4:5], s[14:15], 11
	v_mov_b32_e32 v25, s5
	v_or_b32_e32 v24, s4, v0
	s_cmpk_gt_i32 s14, 0x1fff
	s_mov_b64 s[16:17], -1
	s_cbranch_scc0 .LBB0_973
	v_lshl_add_u64 v[10:11], v[18:19], 0, s[4:5]
	v_lshl_add_u64 v[12:13], v[20:21], 0, s[4:5]
	global_load_dwordx2 v[10:11], v[10:11], off
	s_add_i32 s48, s14, 0xffffe000
	global_load_dwordx2 v[12:13], v[12:13], off
	s_lshl_b64 s[4:5], s[48:49], 13
	s_mov_b64 s[16:17], 0
	s_waitcnt vmcnt(1)
	v_lshlrev_b32_e32 v15, 16, v11
	v_lshlrev_b32_e32 v14, 16, v10
	v_and_b32_e32 v11, 0xffff0000, v11
	v_and_b32_e32 v10, 0xffff0000, v10
	s_waitcnt vmcnt(0)
	v_lshlrev_b32_e32 v17, 16, v13
	v_lshlrev_b32_e32 v16, 16, v12
	v_and_b32_e32 v13, 0xffff0000, v13
	v_and_b32_e32 v12, 0xffff0000, v12
	v_pk_mul_f32 v[10:11], v[10:11], v[12:13]
	s_nop 0
	v_pk_fma_f32 v[10:11], v[14:15], v[16:17], v[10:11]
	s_nop 0
	v_add_f32_e32 v10, v10, v11
	ds_bpermute_b32 v11, v28, v10
	s_waitcnt lgkmcnt(0)
	v_add_f32_e32 v10, v10, v11
	ds_bpermute_b32 v11, v29, v10
	s_waitcnt lgkmcnt(0)
	v_add_f32_e32 v10, v10, v11
	ds_bpermute_b32 v11, v30, v10
	s_waitcnt lgkmcnt(0)
	v_add_f32_e32 v10, v10, v11
	ds_bpermute_b32 v11, v31, v10
	s_waitcnt lgkmcnt(0)
	v_add_f32_e32 v10, v10, v11
	ds_bpermute_b32 v11, v32, v10
	s_waitcnt lgkmcnt(0)
	v_add_f32_e32 v10, v10, v11
	ds_bpermute_b32 v11, v33, v10
	s_waitcnt lgkmcnt(0)
	v_add_f32_e32 v16, v10, v11
	v_lshl_add_u64 v[10:11], v[24:25], 1, s[12:13]
	global_load_dwordx2 v[96:97], v[10:11], off
	s_nop 0
	global_load_dwordx2 v[98:99], v[10:11], off offset:512
	v_lshl_add_u64 v[10:11], v[22:23], 0, s[4:5]
	global_load_dwordx4 v[108:111], v[10:11], off
	v_mov_b32_e32 v106, v16
	v_mov_b32_e32 v107, v17
	global_load_dwordx4 v[120:123], v[10:11], off offset:1024
	v_add_co_u32_e32 v38, vcc, s45, v10
	s_nop 1
	v_addc_co_u32_e32 v39, vcc, 0, v11, vcc
	global_load_dwordx4 v[128:131], v[38:39], off
	global_load_dwordx4 v[132:135], v[38:39], off offset:1024
	v_add_co_u32_e32 v38, vcc, s39, v10
	s_nop 1
	v_addc_co_u32_e32 v39, vcc, 0, v11, vcc
	global_load_dwordx4 v[136:139], v[38:39], off
	global_load_dwordx4 v[140:143], v[38:39], off offset:1024
	v_add_co_u32_e32 v38, vcc, s47, v10
	s_nop 1
	v_addc_co_u32_e32 v39, vcc, 0, v11, vcc
	global_load_dwordx4 v[144:147], v[38:39], off
	global_load_dwordx4 v[148:151], v[38:39], off offset:1024
	v_add_co_u32_e32 v38, vcc, s77, v10
	s_nop 1
	v_addc_co_u32_e32 v39, vcc, 0, v11, vcc
	global_load_dwordx4 v[152:155], v[38:39], off
	global_load_dwordx4 v[156:159], v[38:39], off offset:1024
	v_add_co_u32_e32 v38, vcc, s35, v10
	s_nop 1
	v_addc_co_u32_e32 v39, vcc, 0, v11, vcc
	global_load_dwordx4 v[160:163], v[38:39], off
	global_load_dwordx4 v[164:167], v[38:39], off offset:1024
	s_waitcnt vmcnt(0)
	v_lshlrev_b32_e32 v100, 16, v96
	v_lshlrev_b32_e32 v101, 16, v98
	v_and_b32_e32 v102, 0xffff0000, v98
	v_lshlrev_b32_e32 v103, 16, v99
	v_and_b32_e32 v104, 0xffff0000, v99
	v_and_b32_e32 v98, 0xffff0000, v96
	v_lshlrev_b32_e32 v99, 16, v97
	v_and_b32_e32 v105, 0xffff0000, v97
	v_mov_b32_e32 v112, v100
	v_mov_b32_e32 v113, v98
	v_pk_fma_f32 v[114:115], v[106:107], v[112:113], v[108:109] op_sel_hi:[0,1,1]
	v_mov_b32_e32 v116, v99
	v_mov_b32_e32 v117, v105
	v_pk_fma_f32 v[118:119], v[106:107], v[116:117], v[110:111] op_sel_hi:[0,1,1]
	v_mov_b32_e32 v98, v101
	v_mov_b32_e32 v99, v102
	v_pk_fma_f32 v[124:125], v[106:107], v[98:99], v[120:121] op_sel_hi:[0,1,1]
	v_mov_b32_e32 v100, v103
	v_mov_b32_e32 v101, v104
	v_pk_fma_f32 v[126:127], v[106:107], v[100:101], v[122:123] op_sel_hi:[0,1,1]
	v_pk_add_f32 v[102:103], v[130:131], v[118:119]
	v_pk_add_f32 v[104:105], v[128:129], v[114:115]
	v_pk_add_f32 v[114:115], v[134:135], v[126:127]
	v_pk_add_f32 v[118:119], v[132:133], v[124:125]
	v_pk_add_f32 v[124:125], v[136:137], v[104:105]
	v_pk_add_f32 v[104:105], v[138:139], v[102:103]
	v_pk_add_f32 v[102:103], v[140:141], v[118:119]
	v_pk_add_f32 v[118:119], v[142:143], v[114:115]
	v_pk_add_f32 v[114:115], v[146:147], v[104:105]
	v_pk_add_f32 v[104:105], v[144:145], v[124:125]
	v_pk_add_f32 v[124:125], v[150:151], v[118:119]
	v_pk_add_f32 v[118:119], v[148:149], v[102:103]
	v_pk_add_f32 v[102:103], v[152:153], v[104:105]
	v_pk_add_f32 v[104:105], v[154:155], v[114:115]
	v_pk_add_f32 v[114:115], v[156:157], v[118:119]
	v_pk_add_f32 v[118:119], v[158:159], v[124:125]
	v_pk_add_f32 v[124:125], v[162:163], v[104:105]
	v_pk_add_f32 v[104:105], v[160:161], v[102:103]
	v_pk_add_f32 v[102:103], v[166:167], v[118:119]
	v_mov_b32_e32 v12, v164
	v_mov_b32_e32 v13, v165
	v_mov_b32_e32 v14, v166
	v_mov_b32_e32 v15, v167
	v_mov_b32_e32 v16, v118
	v_mov_b32_e32 v17, v119
	v_mov_b32_e32 v26, v104
	v_mov_b32_e32 v27, v105
	v_mov_b32_e32 v34, v124
	v_mov_b32_e32 v35, v125
	v_mov_b32_e32 v36, v114
	v_mov_b32_e32 v37, v115
	v_mov_b32_e32 v38, v102
	v_mov_b32_e32 v39, v103
	v_add_co_u32_e32 v16, vcc, s74, v10
	v_pk_add_f32 v[36:37], v[12:13], v[36:37]
	s_nop 0
	v_addc_co_u32_e32 v17, vcc, 0, v11, vcc
	global_load_dwordx4 v[96:99], v[16:17], off
	v_mov_b32_e32 v100, v34
	v_mov_b32_e32 v101, v35
	global_load_dwordx4 v[104:107], v[16:17], off offset:1024
	v_mov_b32_e32 v108, v26
	v_mov_b32_e32 v109, v27
	v_mov_b32_e32 v112, v36
	v_mov_b32_e32 v113, v37
	v_add_co_u32_e32 v36, vcc, s66, v10
	v_mov_b32_e32 v116, v38
	v_mov_b32_e32 v117, v39
	s_nop 0
	v_addc_co_u32_e32 v37, vcc, 0, v11, vcc
	global_load_dwordx4 v[120:123], v[36:37], off
	global_load_dwordx4 v[124:127], v[36:37], off offset:1024
	s_waitcnt vmcnt(0)
	v_pk_add_f32 v[102:103], v[100:101], v[98:99]
	v_pk_add_f32 v[110:111], v[108:109], v[96:97]
	v_pk_add_f32 v[114:115], v[112:113], v[104:105]
	v_pk_add_f32 v[104:105], v[116:117], v[106:107]
	v_pk_add_f32 v[106:107], v[102:103], v[122:123]
	v_pk_add_f32 v[122:123], v[110:111], v[120:121]
	v_pk_add_f32 v[120:121], v[104:105], v[126:127]
	v_pk_add_f32 v[104:105], v[114:115], v[124:125]
	v_mov_b32_e32 v10, v122
	v_mov_b32_e32 v11, v123
	v_mov_b32_e32 v12, v106
	v_mov_b32_e32 v13, v107
	v_mov_b32_e32 v14, v104
	v_mov_b32_e32 v15, v105
	v_mov_b32_e32 v16, v120
	v_mov_b32_e32 v17, v121
	v_mov_b32_e32 v26, v110
	v_mov_b32_e32 v27, v111
	v_mov_b32_e32 v34, v124
	v_mov_b32_e32 v35, v125
	v_mov_b32_e32 v36, v126
	v_mov_b32_e32 v37, v127
